# v24 + all wait-placement edits stacked: counted vmcnt in attention K/V staging, hoisted PV reads, counted lgkmcnt in scan step
# baseline (speedup 1.0000x reference)
; __device__ __forceinline__ void finishSM(f32x16& p0, f32x16& p1, float alpha, float& l_reg, bf16x8& pa0, bf16x8& pa1, bf16x8& pa2, bf16x8& pa3) {
; #pragma unroll
;     for (int r = 0; r < 16; ++r) p1[r] = __builtin_amdgcn_exp2f(p1[r]);
;     float ps = 0;
; #pragma unroll
;     for (int r = 0; r < 16; ++r) ps += p0[r];
; #pragma unroll
;     for (int r = 0; r < 16; ++r) ps += p1[r];
;     { auto rr = __builtin_amdgcn_permlane32_swap(__float_as_uint(ps), __float_as_uint(ps), false, false); ps = __uint_as_float(rr[0]) + __uint_as_float(rr[1]); }
;     l_reg = l_reg * alpha + ps;
; __device__ __forceinline__ void qkt(f32x16& p0, f32x16& p1, const char* Ks, const bf16x8* qr, const char* qrl, int r32, int hi) {
;     p0 = f32x16{}; p1 = f32x16{};
; #pragma unroll
;     for (int d0 = 0; d0 < 12; ++d0) { const int cb = (d0 * 16 + hi * 8) * 2;
;         const bf16x8 b0 = *reinterpret_cast<const bf16x8*>(Ks + KSWZ(r32, cb));
;         const bf16x8 b1 = *reinterpret_cast<const bf16x8*>(Ks + KSWZ(32 + r32, cb));
;         const bf16x8 qq = d0 < QREG ? qr[d0 < QREG ? d0 : 0] : *reinterpret_cast<const bf16x8*>(qrl + (d0 - QREG) * 1024);
;         p0 = __builtin_amdgcn_mfma_f32_32x32x16_bf16(b0, qq, p0, 0, 0, 0);
;         p1 = __builtin_amdgcn_mfma_f32_32x32x16_bf16(b1, qq, p1, 0, 0, 0); }
; }
.LBB0_1380:
	v_add_u32_e32 v220, s14, v183
	ds_read_b128 v[64:67], v220
	ds_read_b128 v[68:71], v220 offset:16384
	v_add_u32_e32 v221, s14, v185
	ds_read_b128 v[222:225], v221
	ds_read_b128 v[226:229], v221 offset:16384
	v_add_f32_e32 v140, 0, v136
	s_waitcnt lgkmcnt(3)
	v_mfma_f32_32x32x16_bf16 v[80:95], v[64:67], v[116:119], 0
	v_add_f32_e32 v140, v166, v140
	v_add_f32_e32 v140, v137, v140
	v_add_f32_e32 v140, v167, v140
	v_add_f32_e32 v140, v138, v140
	v_add_f32_e32 v140, v168, v140
	v_add_f32_e32 v140, v139, v140
	v_add_f32_e32 v140, v165, v140
	s_waitcnt lgkmcnt(2)
	v_mfma_f32_32x32x16_bf16 v[64:79], v[68:71], v[116:119], 0
	v_add_f32_e32 v140, v144, v140
	v_add_f32_e32 v140, v146, v140
	v_add_f32_e32 v140, v145, v140
	v_add_f32_e32 v140, v164, v140
	v_exp_f32_e32 v132, v132
	v_add_f32_e32 v140, v141, v140
	v_exp_f32_e32 v133, v133
	s_waitcnt lgkmcnt(1)
	v_mfma_f32_32x32x16_bf16 v[80:95], v[222:225], v[112:115], v[80:95]
	v_add_u32_e32 v222, s14, v187
	v_add_u32_e32 v223, s14, v189
	v_add_f32_e32 v140, v143, v140
	v_exp_f32_e32 v134, v134
	v_add_f32_e32 v140, v142, v140
	v_exp_f32_e32 v135, v135
	v_add_f32_e32 v140, v147, v140
	s_waitcnt lgkmcnt(0)
	v_mfma_f32_32x32x16_bf16 v[64:79], v[226:229], v[112:115], v[64:79]
	ds_read_b128 v[224:227], v222
	ds_read_b128 v[228:231], v222 offset:16384
	v_exp_f32_e32 v122, v122
	v_add_f32_e32 v140, v132, v140
	v_exp_f32_e32 v123, v123
	v_add_f32_e32 v140, v133, v140
	v_exp_f32_e32 v124, v124
	v_add_f32_e32 v140, v134, v140
	s_waitcnt lgkmcnt(1)
	v_mfma_f32_32x32x16_bf16 v[80:95], v[224:227], v[108:111], v[80:95]
	v_exp_f32_e32 v125, v125
	v_add_f32_e32 v140, v135, v140
	v_exp_f32_e32 v126, v126
	v_add_f32_e32 v140, v122, v140
	v_exp_f32_e32 v127, v127
	v_add_f32_e32 v140, v123, v140
	v_exp_f32_e32 v130, v130
	s_waitcnt lgkmcnt(0)
	v_mfma_f32_32x32x16_bf16 v[64:79], v[228:231], v[108:111], v[64:79]
	ds_read_b128 v[224:227], v223
	ds_read_b128 v[228:231], v223 offset:16384
	v_add_f32_e32 v140, v124, v140
	v_exp_f32_e32 v131, v131
	v_add_f32_e32 v140, v125, v140
	v_exp_f32_e32 v120, v120
	v_add_f32_e32 v140, v126, v140
	v_exp_f32_e32 v121, v121
	s_waitcnt lgkmcnt(1)
	v_mfma_f32_32x32x16_bf16 v[80:95], v[224:227], v[104:107], v[80:95]
	v_add_u32_e32 v224, s14, v191
	v_add_u32_e32 v225, s14, v193
	v_add_f32_e32 v140, v127, v140
	v_exp_f32_e32 v128, v128
	v_add_f32_e32 v140, v130, v140
	v_exp_f32_e32 v129, v129
	v_add_f32_e32 v140, v131, v140
	s_waitcnt lgkmcnt(0)
	v_mfma_f32_32x32x16_bf16 v[64:79], v[228:231], v[104:107], v[64:79]
	ds_read_b128 v[226:229], v224
	ds_read_b128 v[230:233], v224 offset:16384
	v_add_f32_e32 v140, v120, v140
	v_add_f32_e32 v140, v121, v140
	v_add_f32_e32 v140, v128, v140
	s_waitcnt lgkmcnt(1)
	v_mfma_f32_32x32x16_bf16 v[80:95], v[226:229], v[100:103], v[80:95]
	s_waitcnt lgkmcnt(0)
	v_mfma_f32_32x32x16_bf16 v[64:79], v[230:233], v[100:103], v[64:79]
	ds_read_b128 v[226:229], v225
	ds_read_b128 v[230:233], v225 offset:16384
	s_waitcnt lgkmcnt(1)
	v_mfma_f32_32x32x16_bf16 v[80:95], v[226:229], v[96:99], v[80:95]
	v_add_u32_e32 v226, s14, v195
	v_add_u32_e32 v227, s14, v197
	s_waitcnt lgkmcnt(0)
	v_mfma_f32_32x32x16_bf16 v[64:79], v[230:233], v[96:99], v[64:79]
	ds_read_b128 v[228:231], v226
	ds_read_b128 v[232:235], v226 offset:16384
	ds_read_b128 v[236:239], v177
	s_waitcnt lgkmcnt(0)
	v_mfma_f32_32x32x16_bf16 v[80:95], v[228:231], v[236:239], v[80:95]
	v_mfma_f32_32x32x16_bf16 v[64:79], v[232:235], v[236:239], v[64:79]
	ds_read_b128 v[228:231], v227
	ds_read_b128 v[232:235], v227 offset:16384
	ds_read_b128 v[236:239], v177 offset:1024
	s_waitcnt lgkmcnt(0)
	v_mfma_f32_32x32x16_bf16 v[80:95], v[228:231], v[236:239], v[80:95]
	v_add_u32_e32 v229, s14, v199
	v_add_u32_e32 v228, s14, v201
	v_mfma_f32_32x32x16_bf16 v[64:79], v[232:235], v[236:239], v[64:79]
	ds_read_b128 v[230:233], v229
	ds_read_b128 v[234:237], v229 offset:16384
	ds_read_b128 v[238:241], v177 offset:2048
	s_waitcnt lgkmcnt(0)
	v_mfma_f32_32x32x16_bf16 v[80:95], v[230:233], v[238:241], v[80:95]
	v_mfma_f32_32x32x16_bf16 v[64:79], v[234:237], v[238:241], v[64:79]
	ds_read_b128 v[230:233], v228
	ds_read_b128 v[234:237], v228 offset:16384
	ds_read_b128 v[238:241], v177 offset:3072
	s_waitcnt lgkmcnt(0)
	v_mfma_f32_32x32x16_bf16 v[80:95], v[230:233], v[238:241], v[80:95]
	v_add_u32_e32 v230, s14, v203
	v_add_u32_e32 v231, s14, v205
	v_mfma_f32_32x32x16_bf16 v[64:79], v[234:237], v[238:241], v[64:79]
	ds_read_b128 v[232:235], v230
	ds_read_b128 v[236:239], v230 offset:16384
	ds_read_b128 v[240:243], v177 offset:4096
	s_waitcnt lgkmcnt(0)
	v_mfma_f32_32x32x16_bf16 v[80:95], v[232:235], v[240:243], v[80:95]
	v_mfma_f32_32x32x16_bf16 v[64:79], v[236:239], v[240:243], v[64:79]
	ds_read_b128 v[232:235], v231
	ds_read_b128 v[236:239], v231 offset:16384
	ds_read_b128 v[240:243], v177 offset:5120
	v_cvt_pk_bf16_f32 v136, v136, v166
	v_cvt_pk_bf16_f32 v137, v137, v167
	v_cvt_pk_bf16_f32 v138, v138, v168
	v_cvt_pk_bf16_f32 v139, v139, v165
	v_cvt_pk_bf16_f32 v144, v144, v146
	v_cvt_pk_bf16_f32 v145, v145, v164
	s_waitcnt lgkmcnt(0)
; #define SBAR() __builtin_amdgcn_sched_barrier(0)
; template <int OFF> __device__ __forceinline__ s16x4 tr_read(int vb) { s16x4 r; asm volatile("ds_read_b64_tr_b16 %0, %1 offset:%2" : "=&v"(r) : "v"(vb), "i"(OFF) : "memory"); return r; }
; __device__ __forceinline__ void finishSM(f32x16& p0, f32x16& p1, float alpha, float& l_reg, bf16x8& pa0, bf16x8& pa1, bf16x8& pa2, bf16x8& pa3) {
;     ...
;     PK4(p0, 0, pa0); PK4(p0, 8, pa1); PK4(p1, 0, pa2); PK4(p1, 8, pa3);
; template <int D0> __device__ __forceinline__ void pv_one(f32x16& od, int vb, bf16x8 pa0, bf16x8 pa1, bf16x8 pa2, bf16x8 pa3) {
;     const s16x4 l0 = tr_read<v_rd_off(D0, 0, 0)>(vb), h0 = tr_read<v_rd_off(D0, 0, 1)>(vb), l1 = tr_read<v_rd_off(D0, 1, 0)>(vb), h1 = tr_read<v_rd_off(D0, 1, 1)>(vb);
;     const s16x4 l2 = tr_read<v_rd_off(D0, 2, 0)>(vb), h2 = tr_read<v_rd_off(D0, 2, 1)>(vb), l3 = tr_read<v_rd_off(D0, 3, 0)>(vb), h3 = tr_read<v_rd_off(D0, 3, 1)>(vb);
;     asm volatile("s_waitcnt lgkmcnt(0)" ::: "memory"); SBAR();
;     ...
;     od = __builtin_amdgcn_mfma_f32_32x32x16_bf16(pa0, PK(l0, h0), od, 0, 0, 0);
;     od = __builtin_amdgcn_mfma_f32_32x32x16_bf16(pa1, PK(l1, h1), od, 0, 0, 0);
;     od = __builtin_amdgcn_mfma_f32_32x32x16_bf16(pa2, PK(l2, h2), od, 0, 0, 0);
;     od = __builtin_amdgcn_mfma_f32_32x32x16_bf16(pa3, PK(l3, h3), od, 0, 0, 0);
;     ...
; }
; __device__ __forceinline__ void pv_d0(f32x16* o, int vb, bf16x8 pa0, bf16x8 pa1, bf16x8 pa2, bf16x8 pa3) {
;     pv_one<0>(o[0], vb, pa0, pa1, pa2, pa3); pv_one<1>(o[1], vb, pa0, pa1, pa2, pa3); pv_one<2>(o[2], vb, pa0, pa1, pa2, pa3); pv_one<3>(o[3], vb, pa0, pa1, pa2, pa3);
; }
	v_mfma_f32_32x32x16_bf16 v[80:95], v[232:235], v[240:243], v[80:95]
	v_add_f32_e32 v232, v129, v140
	v_mov_b32_e32 v233, v232
	v_cvt_pk_bf16_f32 v146, v141, v143
	v_cvt_pk_bf16_f32 v147, v142, v147
	v_cvt_pk_bf16_f32 v234, v132, v133
	v_cvt_pk_bf16_f32 v235, v134, v135
	s_nop 1
	v_permlane32_swap_b32_e32 v232, v233
	v_mfma_f32_32x32x16_bf16 v[64:79], v[236:239], v[240:243], v[64:79]
	ds_read_b64_tr_b16 v[242:243], v176 offset:0
	ds_read_b64_tr_b16 v[244:245], v176 offset:0x800
	ds_read_b64_tr_b16 v[246:247], v176 offset:0x1000
	ds_read_b64_tr_b16 v[248:249], v176 offset:0x1800
	ds_read_b64_tr_b16 v[250:251], v176 offset:0x2000
	ds_read_b64_tr_b16 v[252:253], v176 offset:0x2800
	ds_read_b64_tr_b16 v[208:209], v176 offset:0x3000
	ds_read_b64_tr_b16 v[210:211], v176 offset:0x3800
	v_cvt_pk_bf16_f32 v236, v122, v123
	v_permlane32_swap_b32_e32 v136, v138
	v_cvt_pk_bf16_f32 v237, v124, v125
	v_permlane32_swap_b32_e32 v234, v236
	v_cvt_pk_bf16_f32 v238, v126, v127
	v_cvt_pk_bf16_f32 v239, v130, v131
	v_cvt_pk_bf16_f32 v240, v120, v121
	v_cvt_pk_bf16_f32 v241, v128, v129
	v_permlane32_swap_b32_e32 v137, v139
	v_permlane32_swap_b32_e32 v144, v146
	v_permlane32_swap_b32_e32 v145, v147
	v_permlane32_swap_b32_e32 v235, v237
	v_permlane32_swap_b32_e32 v238, v240
	v_permlane32_swap_b32_e32 v239, v241
	v_lshl_add_u64 v[164:165], s[68:69], 0, v[156:157]
	s_mov_b32 s4, 0x23480000
	v_add_co_u32_e32 v120, vcc, s4, v164
	s_mov_b32 s4, 0x234a0000
	s_nop 0
	v_addc_co_u32_e32 v121, vcc, 0, v165, vcc
	v_add_co_u32_e32 v124, vcc, s4, v164
	v_lshl_add_u64 v[166:167], s[68:69], 0, v[154:155]
	s_nop 0
	v_addc_co_u32_e32 v125, vcc, 0, v165, vcc
	v_add_co_u32_e32 v128, vcc, s97, v166
	v_lshl_add_u64 v[168:169], s[68:69], 0, v[152:153]
	s_nop 0
	v_addc_co_u32_e32 v129, vcc, 0, v167, vcc
	v_add_co_u32_e32 v132, vcc, s97, v168
	v_lshl_add_u64 v[170:171], s[68:69], 0, v[150:151]
	s_nop 0
	v_addc_co_u32_e32 v133, vcc, 0, v169, vcc
	v_add_co_u32_e32 v140, vcc, s97, v170
	global_load_dwordx4 v[120:123], v[120:121], off
	s_nop 0
	global_load_dwordx4 v[124:127], v[124:125], off
	s_nop 0
	global_load_dwordx4 v[128:131], v[128:129], off
	s_nop 0
	global_load_dwordx4 v[132:135], v[132:133], off
	v_addc_co_u32_e32 v141, vcc, 0, v171, vcc
	global_load_dwordx4 v[140:143], v[140:141], off
	s_waitcnt lgkmcnt(0)
	s_nop 0
	v_mfma_f32_32x32x16_bf16 v[0:15], v[136:139], v[242:245], v[0:15]
	v_mfma_f32_32x32x16_bf16 v[0:15], v[144:147], v[246:249], v[0:15]
	v_mfma_f32_32x32x16_bf16 v[0:15], v[234:237], v[250:253], v[0:15]
	v_mfma_f32_32x32x16_bf16 v[0:15], v[238:241], v[208:211], v[0:15]
	ds_read_b64_tr_b16 v[208:209], v176 offset:0x200
	ds_read_b64_tr_b16 v[210:211], v176 offset:0xa00
	ds_read_b64_tr_b16 v[242:243], v176 offset:0x1200
	ds_read_b64_tr_b16 v[244:245], v176 offset:0x1a00
	ds_read_b64_tr_b16 v[246:247], v176 offset:0x2200
	ds_read_b64_tr_b16 v[248:249], v176 offset:0x2a00
	ds_read_b64_tr_b16 v[250:251], v176 offset:0x3200
	ds_read_b64_tr_b16 v[252:253], v176 offset:0x3a00
	s_waitcnt lgkmcnt(0)
	s_nop 0
	v_mfma_f32_32x32x16_bf16 v[48:63], v[136:139], v[208:211], v[48:63]
	ds_read_b64_tr_b16 v[208:209], v176 offset:0x400
	ds_read_b64_tr_b16 v[210:211], v176 offset:0xc00
	v_mfma_f32_32x32x16_bf16 v[48:63], v[144:147], v[242:245], v[48:63]
	ds_read_b64_tr_b16 v[242:243], v176 offset:0x1400
	ds_read_b64_tr_b16 v[244:245], v176 offset:0x1c00
	v_mfma_f32_32x32x16_bf16 v[48:63], v[234:237], v[246:249], v[48:63]
	ds_read_b64_tr_b16 v[246:247], v176 offset:0x2400
	ds_read_b64_tr_b16 v[248:249], v176 offset:0x2c00
	v_mfma_f32_32x32x16_bf16 v[48:63], v[238:241], v[250:253], v[48:63]
	ds_read_b64_tr_b16 v[250:251], v176 offset:0x3400
	ds_read_b64_tr_b16 v[252:253], v176 offset:0x3c00
	s_waitcnt lgkmcnt(0)
	v_mfma_f32_32x32x16_bf16 v[32:47], v[136:139], v[208:211], v[32:47]
	ds_read_b64_tr_b16 v[208:209], v176 offset:0x600
	ds_read_b64_tr_b16 v[210:211], v176 offset:0xe00
	v_mfma_f32_32x32x16_bf16 v[32:47], v[144:147], v[242:245], v[32:47]
	ds_read_b64_tr_b16 v[242:243], v176 offset:0x1600
	ds_read_b64_tr_b16 v[244:245], v176 offset:0x1e00
	v_mfma_f32_32x32x16_bf16 v[32:47], v[234:237], v[246:249], v[32:47]
	ds_read_b64_tr_b16 v[246:247], v176 offset:0x2600
	ds_read_b64_tr_b16 v[248:249], v176 offset:0x2e00
	v_mfma_f32_32x32x16_bf16 v[32:47], v[238:241], v[250:253], v[32:47]
	ds_read_b64_tr_b16 v[250:251], v176 offset:0x3600
	ds_read_b64_tr_b16 v[252:253], v176 offset:0x3e00
	s_waitcnt lgkmcnt(0)
	v_mfma_f32_32x32x16_bf16 v[16:31], v[136:139], v[208:211], v[16:31]
	v_max_f32_e32 v136, v81, v81
	v_max_f32_e32 v137, v80, v80
	v_max_f32_e32 v136, v137, v136
	v_max3_f32 v136, v136, v82, v83
	v_max3_f32 v136, v136, v84, v85
	v_max3_f32 v136, v136, v86, v87
	v_max3_f32 v136, v136, v88, v89
	v_max3_f32 v136, v136, v90, v91
	v_mfma_f32_32x32x16_bf16 v[16:31], v[144:147], v[242:245], v[16:31]
	v_max3_f32 v136, v136, v92, v93
	v_max3_f32 v136, v136, v94, v95
	v_max3_f32 v136, v136, v64, v65
	v_max3_f32 v136, v136, v66, v67
	v_max3_f32 v136, v136, v68, v69
	v_max3_f32 v136, v136, v70, v71
	v_max3_f32 v136, v136, v72, v73
	v_max3_f32 v136, v136, v74, v75
	v_mfma_f32_32x32x16_bf16 v[16:31], v[234:237], v[246:249], v[16:31]
	v_max3_f32 v136, v136, v76, v77
	v_max3_f32 v136, v136, v78, v79
	v_mov_b32_e32 v137, v136
	s_nop 1
	v_permlane32_swap_b32_e32 v136, v137
	v_max_f32_e32 v137, v137, v137
	v_max_f32_e32 v136, v136, v136
	v_max_f32_e32 v136, v136, v137
	v_sub_f32_e32 v137, v136, v158
	v_cmp_ge_f32_e32 vcc, s62, v137
	v_max_f32_e32 v137, v158, v158
	v_mfma_f32_32x32x16_bf16 v[16:31], v[238:241], v[250:253], v[16:31]
	v_max_f32_e32 v136, v137, v136
	v_sub_f32_e32 v137, v158, v136
	v_exp_f32_e32 v137, v137
	s_cmp_eq_u64 vcc, exec
	s_cselect_b64 s[4:5], -1, 0
	s_barrier
; #define SBAR() __builtin_amdgcn_sched_barrier(0)
; #define SWRITE(b) do { *(bf16x8*)(V_lds + (b) * SHM_V + vst0) = vs0; *(bf16x8*)(V_lds + (b) * SHM_V + vst1) = vs1; \
;     *(bf16x8*)(K_lds + (b) * SHM_K + KSWZ(kr0, kc0 * 16)) = ks0; *(bf16x8*)(K_lds + (b) * SHM_K + KSWZ(kr1, kc1 * 16)) = ks1; *(bf16x8*)(K_lds + (b) * SHM_K + KSWZ(kr2, kc2 * 16)) = ks2; } while (0)
; #define SWAIT() asm volatile("s_waitcnt vmcnt(0)" ::: "memory")
; #define RESC(a) do { if (__any((a) < 1.f)) { if (hi == 0) al_l[r32] = (a); asm volatile("s_waitcnt lgkmcnt(0)" ::: "memory"); \
;     _Pragma("unroll") for (int d = 0; d < 4; ++d) _Pragma("unroll") for (int r = 0; r < 16; ++r) o[d][r] *= al_l[crow(r, hi)]; } } while (0)
; __device__ __forceinline__ void attn_unit(const bf16_t* __restrict__ Qb, const bf16_t* __restrict__ Kh, const bf16_t* __restrict__ Vh, bf16_t* __restrict__ Ob, int seq, char* lds) {
;     ...
;     f32x16 pA0, pA1, pB0, pB1; float mnA, mnB, alA, alB; bf16x8 pa0, pa1, pa2, pa3; const int NT = seq / KVBLK;
;     SLOAD(0); SWAIT(); SWRITE(0); __syncthreads();
;     qkt(pA0, pA1, K_lds, qr, qrl, r32, hi); partialSM(pA0, pA1, m_reg, mnA, alA);
;     SLOAD(KVBLK);
;     SWAIT(); SWRITE(1); __syncthreads();
;     for (int j = 1; j + 1 < NT; j += 2) {
;         SBAR(); qkt(pB0, pB1, K_lds + SHM_K, qr, qrl, r32, hi);
;         finishSM(pA0, pA1, alA, l_reg, pa0, pa1, pa2, pa3); SBAR();
;         SLOAD((j + 1) * KVBLK); SBAR();
;         pv_d0(o, vb0, pa0, pa1, pa2, pa3); partialSM(pB0, pB1, m_reg, mnB, alB);
;         __syncthreads(); SWAIT(); SWRITE(0);
;         RESC(alB); __syncthreads();
	v_cndmask_b32_e64 v234, v137, 1.0, s[4:5]
	v_cmp_gt_f32_e32 vcc, 1.0, v234
	s_waitcnt vmcnt(4)
	ds_write_b128 v178, v[120:123]
	s_waitcnt vmcnt(3)
	ds_write_b128 v179, v[124:127]
	s_waitcnt vmcnt(2)
	ds_write_b128 v180, v[128:131] offset:32768
	s_waitcnt vmcnt(1)
	ds_write_b128 v181, v[132:135] offset:32768
	s_waitcnt vmcnt(0)
	ds_write_b128 v182, v[140:143] offset:32768
	s_cbranch_vccz .LBB0_1384
	s_and_saveexec_b64 s[12:13], s[2:3]
	ds_write_b32 v173, v234 offset:128
	s_or_b64 exec, exec, s[12:13]
	s_waitcnt lgkmcnt(0)
	v_add_u32_e32 v132, v149, v160
	ds_read_b128 v[120:123], v132 offset:224
	ds_read_b128 v[124:127], v132 offset:192
	ds_read_b128 v[128:131], v132 offset:160
	ds_read_b128 v[132:135], v132 offset:128
	s_waitcnt lgkmcnt(3)
	v_pk_mul_f32 v[12:13], v[12:13], v[120:121]
	s_waitcnt lgkmcnt(2)
	v_pk_mul_f32 v[8:9], v[8:9], v[124:125]
	s_waitcnt lgkmcnt(1)
	v_pk_mul_f32 v[4:5], v[4:5], v[128:129]
	v_pk_mul_f32 v[14:15], v[14:15], v[122:123]
	v_pk_mul_f32 v[10:11], v[10:11], v[126:127]
	v_pk_mul_f32 v[6:7], v[6:7], v[130:131]
	s_waitcnt lgkmcnt(0)
	v_pk_mul_f32 v[2:3], v[2:3], v[134:135]
	v_pk_mul_f32 v[0:1], v[0:1], v[132:133]
	v_pk_mul_f32 v[60:61], v[60:61], v[120:121]
	v_pk_mul_f32 v[56:57], v[56:57], v[124:125]
	v_pk_mul_f32 v[52:53], v[52:53], v[128:129]
	v_pk_mul_f32 v[62:63], v[62:63], v[122:123]
	v_pk_mul_f32 v[58:59], v[58:59], v[126:127]
	v_pk_mul_f32 v[54:55], v[54:55], v[130:131]
	v_pk_mul_f32 v[50:51], v[50:51], v[134:135]
	v_pk_mul_f32 v[48:49], v[48:49], v[132:133]
	v_pk_mul_f32 v[44:45], v[44:45], v[120:121]
	v_pk_mul_f32 v[40:41], v[40:41], v[124:125]
	v_pk_mul_f32 v[36:37], v[36:37], v[128:129]
	v_pk_mul_f32 v[46:47], v[46:47], v[122:123]
	v_pk_mul_f32 v[42:43], v[42:43], v[126:127]
	v_pk_mul_f32 v[38:39], v[38:39], v[130:131]
	v_pk_mul_f32 v[34:35], v[34:35], v[134:135]
	v_pk_mul_f32 v[32:33], v[32:33], v[132:133]
	v_pk_mul_f32 v[28:29], v[28:29], v[120:121]
	v_pk_mul_f32 v[24:25], v[24:25], v[124:125]
	v_pk_mul_f32 v[20:21], v[20:21], v[128:129]
	v_pk_mul_f32 v[30:31], v[30:31], v[122:123]
	v_pk_mul_f32 v[26:27], v[26:27], v[126:127]
	v_pk_mul_f32 v[22:23], v[22:23], v[130:131]
	v_pk_mul_f32 v[18:19], v[18:19], v[134:135]
	v_pk_mul_f32 v[16:17], v[16:17], v[132:133]
